# code placement: the six GEMM K-loop heads aligned to 64 bytes
# speedup vs baseline: 1.0061x; 1.0031x over previous
.LBB0_65:
	s_ashr_i32 s31, s30, 31
	s_nop 1
	s_lshl_b64 s[26:27], s[30:31], 19
	v_readlane_b32 s6, v253, 18
	v_readlane_b32 s7, v253, 19
	s_add_u32 s34, s6, s26
	s_addc_u32 s35, s7, s27
	s_cmp_eq_u32 s101, 2
	s_cselect_b32 s26, 0x40000, 0
	s_add_u32 s34, s34, s26
	s_addc_u32 s35, s35, 0
	s_and_b64 s[26:27], s[44:45], exec
	s_cselect_b32 s31, s35, s41
	s_cselect_b32 s80, s34, s40
	s_ashr_i32 s29, s28, 31
	s_lshl_b64 s[26:27], s[28:29], 19
	s_add_u32 s36, s48, s26
	s_addc_u32 s37, s49, s27
	s_and_b64 s[26:27], s[44:45], exec
	s_cselect_b32 s29, s37, s43
	s_cselect_b32 vcc_lo, s36, s42
	s_add_u32 s40, s40, 0x40080
	s_addc_u32 s41, s41, 0
	s_add_u32 s26, s42, 0x100
	v_mov_b32_e32 v0, 0
	s_addc_u32 s27, s43, 0
	s_mov_b32 s96, -2
	v_mov_b32_e32 v1, v0
	v_mov_b64_e32 v[2:3], 0
	v_mov_b64_e32 v[8:9], 0
	v_mov_b64_e32 v[10:11], 0
	v_mov_b64_e32 v[16:17], 0
	v_mov_b64_e32 v[18:19], 0
	v_mov_b64_e32 v[24:25], 0
	v_mov_b64_e32 v[26:27], 0
	v_mov_b64_e32 v[32:33], 0
	v_mov_b64_e32 v[34:35], 0
	v_mov_b64_e32 v[40:41], 0
	v_mov_b64_e32 v[42:43], 0
	v_mov_b64_e32 v[48:49], 0
	v_mov_b64_e32 v[50:51], 0
	v_mov_b64_e32 v[56:57], 0
	v_mov_b64_e32 v[58:59], 0
	v_mov_b64_e32 v[4:5], 0
	v_mov_b64_e32 v[6:7], 0
	v_mov_b64_e32 v[12:13], 0
	v_mov_b64_e32 v[14:15], 0
	v_mov_b64_e32 v[20:21], 0
	v_mov_b64_e32 v[22:23], 0
	v_mov_b64_e32 v[28:29], 0
	v_mov_b64_e32 v[30:31], 0
	v_mov_b64_e32 v[36:37], 0
	v_mov_b64_e32 v[38:39], 0
	v_mov_b64_e32 v[44:45], 0
	v_mov_b64_e32 v[46:47], 0
	v_mov_b64_e32 v[52:53], 0
	v_mov_b64_e32 v[54:55], 0
	v_mov_b64_e32 v[60:61], 0
	v_mov_b64_e32 v[62:63], 0
	v_mov_b64_e32 v[64:65], 0
	v_mov_b64_e32 v[66:67], 0
	v_mov_b64_e32 v[72:73], 0
	v_mov_b64_e32 v[74:75], 0
	v_mov_b64_e32 v[80:81], 0
	v_mov_b64_e32 v[82:83], 0
	v_mov_b64_e32 v[88:89], 0
	v_mov_b64_e32 v[90:91], 0
	v_mov_b64_e32 v[96:97], 0
	v_mov_b64_e32 v[98:99], 0
	v_mov_b64_e32 v[104:105], 0
	v_mov_b64_e32 v[106:107], 0
	v_mov_b64_e32 v[112:113], 0
	v_mov_b64_e32 v[114:115], 0
	v_mov_b64_e32 v[120:121], 0
	v_mov_b64_e32 v[122:123], 0
	v_mov_b64_e32 v[68:69], 0
	v_mov_b64_e32 v[70:71], 0
	v_mov_b64_e32 v[76:77], 0
	v_mov_b64_e32 v[78:79], 0
	v_mov_b64_e32 v[84:85], 0
	v_mov_b64_e32 v[86:87], 0
	v_mov_b64_e32 v[92:93], 0
	v_mov_b64_e32 v[94:95], 0
	v_mov_b64_e32 v[100:101], 0
	v_mov_b64_e32 v[102:103], 0
	v_mov_b64_e32 v[108:109], 0
	v_mov_b64_e32 v[110:111], 0
	v_mov_b64_e32 v[116:117], 0
	v_mov_b64_e32 v[118:119], 0
	v_mov_b64_e32 v[124:125], 0
	v_mov_b64_e32 v[126:127], 0
	s_nop 1
	v_add_u32_e32 v230, 0x10000, v140
	.p2align 6

.LBB0_93:
	s_add_u32 s30, s30, 0x80
	s_addc_u32 s31, s31, 0
	s_add_u32 s26, s34, 0x100
	v_mov_b32_e32 v0, 0
	s_addc_u32 s27, s35, 0
	s_mov_b32 s34, 0
	v_mov_b32_e32 v1, v0
	v_mov_b64_e32 v[2:3], 0
	v_mov_b64_e32 v[4:5], 0
	v_mov_b64_e32 v[6:7], 0
	v_mov_b64_e32 v[8:9], 0
	v_mov_b64_e32 v[10:11], 0
	v_mov_b64_e32 v[12:13], 0
	v_mov_b64_e32 v[14:15], 0
	v_mov_b64_e32 v[16:17], 0
	v_mov_b64_e32 v[18:19], 0
	v_mov_b64_e32 v[20:21], 0
	v_mov_b64_e32 v[22:23], 0
	v_mov_b64_e32 v[24:25], 0
	v_mov_b64_e32 v[26:27], 0
	v_mov_b64_e32 v[28:29], 0
	v_mov_b64_e32 v[30:31], 0
	v_mov_b64_e32 v[32:33], 0
	v_mov_b64_e32 v[34:35], 0
	v_mov_b64_e32 v[36:37], 0
	v_mov_b64_e32 v[38:39], 0
	v_mov_b64_e32 v[40:41], 0
	v_mov_b64_e32 v[42:43], 0
	v_mov_b64_e32 v[44:45], 0
	v_mov_b64_e32 v[46:47], 0
	v_mov_b64_e32 v[48:49], 0
	v_mov_b64_e32 v[50:51], 0
	v_mov_b64_e32 v[52:53], 0
	v_mov_b64_e32 v[54:55], 0
	v_mov_b64_e32 v[56:57], 0
	v_mov_b64_e32 v[58:59], 0
	v_mov_b64_e32 v[60:61], 0
	v_mov_b64_e32 v[62:63], 0
	v_mov_b64_e32 v[64:65], 0
	v_mov_b64_e32 v[66:67], 0
	v_mov_b64_e32 v[68:69], 0
	v_mov_b64_e32 v[70:71], 0
	v_mov_b64_e32 v[72:73], 0
	v_mov_b64_e32 v[74:75], 0
	v_mov_b64_e32 v[76:77], 0
	v_mov_b64_e32 v[78:79], 0
	v_mov_b64_e32 v[80:81], 0
	v_mov_b64_e32 v[82:83], 0
	v_mov_b64_e32 v[84:85], 0
	v_mov_b64_e32 v[86:87], 0
	v_mov_b64_e32 v[88:89], 0
	v_mov_b64_e32 v[90:91], 0
	v_mov_b64_e32 v[92:93], 0
	v_mov_b64_e32 v[94:95], 0
	v_mov_b64_e32 v[96:97], 0
	v_mov_b64_e32 v[98:99], 0
	v_mov_b64_e32 v[100:101], 0
	v_mov_b64_e32 v[102:103], 0
	v_mov_b64_e32 v[104:105], 0
	v_mov_b64_e32 v[106:107], 0
	v_mov_b64_e32 v[108:109], 0
	v_mov_b64_e32 v[110:111], 0
	v_mov_b64_e32 v[112:113], 0
	v_mov_b64_e32 v[114:115], 0
	v_mov_b64_e32 v[116:117], 0
	v_mov_b64_e32 v[118:119], 0
	v_mov_b64_e32 v[120:121], 0
	v_mov_b64_e32 v[122:123], 0
	v_mov_b64_e32 v[124:125], 0
	v_mov_b64_e32 v[126:127], 0
	s_cmp_lg_u32 s100, 0
	s_cselect_b64 vcc, -1, 0
	v_add_u32_e32 v251, 0x10000, v142
	.p2align 6

.LBB0_110:
	s_lshl_b32 s36, s43, 8
	s_ashr_i32 s45, s44, 31
	s_ashr_i32 s37, s36, 31
	s_nop 1
	s_lshl_b64 s[38:39], s[44:45], 19
	s_lshl_b64 s[36:37], s[36:37], 1
	v_readlane_b32 s8, v253, 20
	v_readlane_b32 s9, v253, 21
	s_add_u32 s27, s8, s38
	s_addc_u32 s33, s9, s39
	s_add_u32 s48, s27, s36
	s_addc_u32 s49, s33, s37
	s_lshl_b32 s27, s43, 10
	s_lshl_b32 s33, s42, 8
	s_add_i32 s36, s33, s27
	s_nop 1
	s_ashr_i32 s37, s36, 31
	s_lshl_b64 s[36:37], s[36:37], 9
	v_readlane_b32 s4, v255, 47
	s_add_u32 s50, s66, s36
	v_readlane_b32 s5, v255, 48
	s_addc_u32 s51, s67, s37
	s_andn2_b64 vcc, exec, s[4:5]
	s_nop 1
	s_cbranch_vccnz .LBB0_114
	s_and_b64 s[30:31], s[30:31], exec
	s_cselect_b32 s27, s49, s23
	s_cselect_b32 s33, s48, s22
	s_cselect_b32 s36, s51, s29
	s_cselect_b32 s37, s50, s28
	s_add_u32 s22, s22, 0x40080
	s_addc_u32 s23, s23, 0
	s_add_u32 s38, s28, 0x100
	s_mov_b32 s5, s67
	s_mov_b32 s4, s66
	s_addc_u32 s39, s29, 0
	s_mov_b32 s28, 0
	.p2align 6

.LBB0_233:
	s_add_i32 s62, s62, 1
	s_waitcnt lgkmcnt(0)
	s_mul_i32 s0, s62, s90
	s_mov_b64 s[26:27], s[22:23]
	s_add_i32 s22, s0, s96
	s_cmpk_lt_i32 s22, 0x100
	s_cselect_b64 s[30:31], -1, 0
	s_cmpk_gt_i32 s22, 0xff
	s_mov_b64 s[34:35], s[28:29]
	s_mov_b32 s20, s69
	s_mov_b32 s29, s68
	s_mov_b32 s28, s65
	s_cselect_b64 s[0:1], -1, 0
	s_and_b32 s68, s22, 3
	s_bfe_u32 s69, s22, 0x30002
	s_ashr_i32 s65, s22, 5
	s_and_b64 s[22:23], s[30:31], exec
	s_cselect_b32 s29, s68, s29
	s_cselect_b32 s28, s65, s28
	s_cselect_b32 s22, s69, s20
	s_lshl_b32 s36, s29, 10
	s_ashr_i32 s23, s22, 31
	s_ashr_i32 s37, s36, 31
	s_nop 1
	s_lshl_b64 s[22:23], s[22:23], 21
	s_lshl_b64 s[36:37], s[36:37], 1
	v_readlane_b32 s16, v253, 12
	v_readlane_b32 s17, v253, 13
	s_add_u32 s20, s16, s22
	s_addc_u32 s23, s17, s23
	s_add_u32 s22, s20, s36
	s_addc_u32 s23, s23, s37
	s_and_b64 vcc, s[30:31], exec
	s_cselect_b32 vcc_lo, s23, s27
	s_cselect_b32 vcc_hi, s22, s26
	s_ashr_i32 s29, s28, 31
	s_lshl_b64 s[28:29], s[28:29], 13
	s_add_u32 s20, s78, s28
	s_addc_u32 s29, s79, s29
	s_add_u32 s28, s20, s36
	s_addc_u32 s29, s29, s37
	s_and_b64 s[30:31], s[30:31], exec
	s_cselect_b32 s33, s29, s35
	s_cselect_b32 s20, s28, s34
	s_add_u32 s30, s26, 0x100080
	s_addc_u32 s31, s27, 0
	s_add_u32 s26, s34, 0x100
	v_mov_b32_e32 v0, 0
	s_addc_u32 s27, s35, 0
	s_mov_b32 s96, -2
	v_mov_b32_e32 v1, v0
	v_mov_b64_e32 v[2:3], 0
	v_mov_b64_e32 v[4:5], 0
	v_mov_b64_e32 v[6:7], 0
	v_mov_b64_e32 v[8:9], 0
	v_mov_b64_e32 v[10:11], 0
	v_mov_b64_e32 v[12:13], 0
	v_mov_b64_e32 v[14:15], 0
	v_mov_b64_e32 v[16:17], 0
	v_mov_b64_e32 v[18:19], 0
	v_mov_b64_e32 v[20:21], 0
	v_mov_b64_e32 v[22:23], 0
	v_mov_b64_e32 v[24:25], 0
	v_mov_b64_e32 v[26:27], 0
	v_mov_b64_e32 v[28:29], 0
	v_mov_b64_e32 v[30:31], 0
	v_mov_b64_e32 v[32:33], 0
	v_mov_b64_e32 v[34:35], 0
	v_mov_b64_e32 v[36:37], 0
	v_mov_b64_e32 v[38:39], 0
	v_mov_b64_e32 v[40:41], 0
	v_mov_b64_e32 v[42:43], 0
	v_mov_b64_e32 v[44:45], 0
	v_mov_b64_e32 v[46:47], 0
	v_mov_b64_e32 v[48:49], 0
	v_mov_b64_e32 v[50:51], 0
	v_mov_b64_e32 v[52:53], 0
	v_mov_b64_e32 v[54:55], 0
	v_mov_b64_e32 v[56:57], 0
	v_mov_b64_e32 v[58:59], 0
	v_mov_b64_e32 v[60:61], 0
	v_mov_b64_e32 v[62:63], 0
	v_mov_b64_e32 v[64:65], 0
	v_mov_b64_e32 v[66:67], 0
	v_mov_b64_e32 v[68:69], 0
	v_mov_b64_e32 v[70:71], 0
	v_mov_b64_e32 v[72:73], 0
	v_mov_b64_e32 v[74:75], 0
	v_mov_b64_e32 v[76:77], 0
	v_mov_b64_e32 v[78:79], 0
	v_mov_b64_e32 v[80:81], 0
	v_mov_b64_e32 v[82:83], 0
	v_mov_b64_e32 v[84:85], 0
	v_mov_b64_e32 v[86:87], 0
	v_mov_b64_e32 v[88:89], 0
	v_mov_b64_e32 v[90:91], 0
	v_mov_b64_e32 v[92:93], 0
	v_mov_b64_e32 v[94:95], 0
	v_mov_b64_e32 v[96:97], 0
	v_mov_b64_e32 v[98:99], 0
	v_mov_b64_e32 v[100:101], 0
	v_mov_b64_e32 v[102:103], 0
	v_mov_b64_e32 v[104:105], 0
	v_mov_b64_e32 v[106:107], 0
	v_mov_b64_e32 v[108:109], 0
	v_mov_b64_e32 v[110:111], 0
	v_mov_b64_e32 v[112:113], 0
	v_mov_b64_e32 v[114:115], 0
	v_mov_b64_e32 v[116:117], 0
	v_mov_b64_e32 v[118:119], 0
	v_mov_b64_e32 v[120:121], 0
	v_mov_b64_e32 v[122:123], 0
	v_mov_b64_e32 v[124:125], 0
	v_mov_b64_e32 v[126:127], 0
	s_nop 1
	v_add_u32_e32 v230, 0x10000, v143
	.p2align 6

.LBB0_244:
	s_add_i32 s55, s55, 1
	s_mov_b64 s[26:27], s[22:23]
	s_mul_i32 s22, s55, s90
	s_mov_b32 s20, s58
	s_add_i32 s58, s22, s0
	s_cmp_lt_i32 s58, 8
	s_cselect_b32 s22, s58, s20
	s_ashr_i32 s23, s22, 31
	s_nop 1
	s_lshl_b64 s[22:23], s[22:23], 10
	v_readlane_b32 s12, v253, 24
	v_readlane_b32 s13, v253, 25
	s_add_u32 s22, s12, s22
	s_addc_u32 s23, s13, s23
	s_cmp_lt_i32 s58, 8
	s_cselect_b32 s20, s23, s27
	s_cselect_b32 s60, s22, s26
	s_cmp_gt_i32 s58, 7
	s_cselect_b64 s[28:29], -1, 0
	s_add_u32 s26, s26, 0x100
	v_mov_b32_e32 v0, 0
	v_readlane_b32 s30, v255, 17
	s_nop 1
	s_addc_u32 s27, s27, 0
	s_mov_b32 s61, -2
	v_readlane_b32 s31, v255, 18
	v_mov_b32_e32 v1, v0
	v_mov_b64_e32 v[2:3], 0
	v_mov_b64_e32 v[4:5], 0
	v_mov_b64_e32 v[6:7], 0
	v_mov_b64_e32 v[8:9], 0
	v_mov_b64_e32 v[10:11], 0
	v_mov_b64_e32 v[12:13], 0
	v_mov_b64_e32 v[14:15], 0
	v_mov_b64_e32 v[16:17], 0
	v_mov_b64_e32 v[18:19], 0
	v_mov_b64_e32 v[20:21], 0
	v_mov_b64_e32 v[22:23], 0
	v_mov_b64_e32 v[24:25], 0
	v_mov_b64_e32 v[26:27], 0
	v_mov_b64_e32 v[28:29], 0
	v_mov_b64_e32 v[30:31], 0
	v_mov_b64_e32 v[32:33], 0
	v_mov_b64_e32 v[34:35], 0
	v_mov_b64_e32 v[36:37], 0
	v_mov_b64_e32 v[38:39], 0
	v_mov_b64_e32 v[40:41], 0
	v_mov_b64_e32 v[42:43], 0
	v_mov_b64_e32 v[44:45], 0
	v_mov_b64_e32 v[46:47], 0
	v_mov_b64_e32 v[48:49], 0
	v_mov_b64_e32 v[50:51], 0
	v_mov_b64_e32 v[52:53], 0
	v_mov_b64_e32 v[54:55], 0
	v_mov_b64_e32 v[56:57], 0
	v_mov_b64_e32 v[58:59], 0
	v_mov_b64_e32 v[60:61], 0
	v_mov_b64_e32 v[62:63], 0
	v_mov_b64_e32 v[64:65], 0
	v_mov_b64_e32 v[66:67], 0
	v_mov_b64_e32 v[68:69], 0
	v_mov_b64_e32 v[70:71], 0
	v_mov_b64_e32 v[72:73], 0
	v_mov_b64_e32 v[74:75], 0
	v_mov_b64_e32 v[76:77], 0
	v_mov_b64_e32 v[78:79], 0
	v_mov_b64_e32 v[80:81], 0
	v_mov_b64_e32 v[82:83], 0
	v_mov_b64_e32 v[84:85], 0
	v_mov_b64_e32 v[86:87], 0
	v_mov_b64_e32 v[88:89], 0
	v_mov_b64_e32 v[90:91], 0
	v_mov_b64_e32 v[92:93], 0
	v_mov_b64_e32 v[94:95], 0
	v_mov_b64_e32 v[96:97], 0
	v_mov_b64_e32 v[98:99], 0
	v_mov_b64_e32 v[100:101], 0
	v_mov_b64_e32 v[102:103], 0
	v_mov_b64_e32 v[104:105], 0
	v_mov_b64_e32 v[106:107], 0
	v_mov_b64_e32 v[108:109], 0
	v_mov_b64_e32 v[110:111], 0
	v_mov_b64_e32 v[112:113], 0
	v_mov_b64_e32 v[114:115], 0
	v_mov_b64_e32 v[116:117], 0
	v_mov_b64_e32 v[118:119], 0
	v_mov_b64_e32 v[120:121], 0
	v_mov_b64_e32 v[122:123], 0
	v_mov_b64_e32 v[124:125], 0
	v_mov_b64_e32 v[126:127], 0
	v_readlane_b32 s78, v253, 14
	v_readlane_b32 s79, v253, 15
	s_nop 1
	v_readlane_b32 s65, v253, 1
	s_nop 1
	v_readlane_b32 s68, v253, 4
	v_readlane_b32 s69, v253, 5
	s_nop 1
	v_add_u32_e32 v230, 0x10000, v143
	.p2align 6

.LBB0_298:
	s_lshl_b32 s20, s55, 8
	s_addk_i32 s20, 0x1800
	s_cmp_eq_u32 s54, 0
	s_nop 1
	s_cselect_b32 s26, s55, s20
	v_readlane_b32 s6, v253, 18
	v_readlane_b32 s7, v253, 19
	s_cselect_b32 s20, 19, 11
	s_cselect_b32 s34, s7, s57
	s_cselect_b32 s35, s6, s56
	s_cselect_b32 s36, s56, s6
	s_cselect_b32 s37, s57, s7
	s_ashr_i32 s27, s26, 31
	s_lshl_b64 s[26:27], s[26:27], s20
	s_add_u32 s42, s35, s26
	s_addc_u32 s43, s34, s27
	s_cmp_eq_u32 s101, 2
	s_cselect_b32 s26, 0x40000, 0
	s_add_u32 s42, s42, s26
	s_addc_u32 s43, s43, 0
	s_and_b64 s[26:27], s[30:31], exec
	s_cselect_b32 s20, s43, s1
	s_cselect_b32 s34, s42, s0
	s_ashr_i32 s41, s40, 31
	s_lshl_b64 s[26:27], s[40:41], 19
	s_add_u32 s44, s36, s26
	s_addc_u32 s45, s37, s27
	s_and_b64 s[26:27], s[30:31], exec
	s_cselect_b32 s35, s45, s29
	s_cselect_b32 s36, s44, s28
	s_add_u32 s0, s0, 0x40080
	s_addc_u32 s1, s1, 0
	s_add_u32 s37, s28, 0x100
	v_mov_b32_e32 v0, 0
	s_addc_u32 s26, s29, 0
	s_mov_b32 s27, -2
	v_mov_b32_e32 v1, v0
	v_mov_b64_e32 v[2:3], 0
	v_mov_b64_e32 v[4:5], 0
	v_mov_b64_e32 v[6:7], 0
	v_mov_b64_e32 v[8:9], 0
	v_mov_b64_e32 v[10:11], 0
	v_mov_b64_e32 v[12:13], 0
	v_mov_b64_e32 v[14:15], 0
	v_mov_b64_e32 v[16:17], 0
	v_mov_b64_e32 v[18:19], 0
	v_mov_b64_e32 v[20:21], 0
	v_mov_b64_e32 v[22:23], 0
	v_mov_b64_e32 v[24:25], 0
	v_mov_b64_e32 v[26:27], 0
	v_mov_b64_e32 v[28:29], 0
	v_mov_b64_e32 v[30:31], 0
	v_mov_b64_e32 v[32:33], 0
	v_mov_b64_e32 v[34:35], 0
	v_mov_b64_e32 v[36:37], 0
	v_mov_b64_e32 v[38:39], 0
	v_mov_b64_e32 v[40:41], 0
	v_mov_b64_e32 v[42:43], 0
	v_mov_b64_e32 v[44:45], 0
	v_mov_b64_e32 v[46:47], 0
	v_mov_b64_e32 v[48:49], 0
	v_mov_b64_e32 v[50:51], 0
	v_mov_b64_e32 v[52:53], 0
	v_mov_b64_e32 v[54:55], 0
	v_mov_b64_e32 v[56:57], 0
	v_mov_b64_e32 v[58:59], 0
	v_mov_b64_e32 v[60:61], 0
	v_mov_b64_e32 v[62:63], 0
	v_mov_b64_e32 v[64:65], 0
	v_mov_b64_e32 v[66:67], 0
	v_mov_b64_e32 v[68:69], 0
	v_mov_b64_e32 v[70:71], 0
	v_mov_b64_e32 v[72:73], 0
	v_mov_b64_e32 v[74:75], 0
	v_mov_b64_e32 v[76:77], 0
	v_mov_b64_e32 v[78:79], 0
	v_mov_b64_e32 v[80:81], 0
	v_mov_b64_e32 v[82:83], 0
	v_mov_b64_e32 v[84:85], 0
	v_mov_b64_e32 v[86:87], 0
	v_mov_b64_e32 v[88:89], 0
	v_mov_b64_e32 v[90:91], 0
	v_mov_b64_e32 v[92:93], 0
	v_mov_b64_e32 v[94:95], 0
	v_mov_b64_e32 v[96:97], 0
	v_mov_b64_e32 v[98:99], 0
	v_mov_b64_e32 v[100:101], 0
	v_mov_b64_e32 v[102:103], 0
	v_mov_b64_e32 v[104:105], 0
	v_mov_b64_e32 v[106:107], 0
	v_mov_b64_e32 v[108:109], 0
	v_mov_b64_e32 v[110:111], 0
	v_mov_b64_e32 v[112:113], 0
	v_mov_b64_e32 v[114:115], 0
	v_mov_b64_e32 v[116:117], 0
	v_mov_b64_e32 v[118:119], 0
	v_mov_b64_e32 v[120:121], 0
	v_mov_b64_e32 v[122:123], 0
	v_mov_b64_e32 v[124:125], 0
	v_mov_b64_e32 v[126:127], 0
	s_nop 1
	v_add_u32_e32 v230, 0x10000, v143
	.p2align 6
